# out-proj GEMM K-loops: remaining temporary 64-bit address adds (carry-pair base) also folded into scalar-base LDS-DMA loads
# baseline (speedup 1.0000x reference)
; #define PG8_STAGE(bufoff, gbase, voff) do { _Pragma("unroll") for (int _i = 0; _i < 2; ++_i) \
;         __builtin_amdgcn_global_load_lds((const unsigned*)((const char*)(gbase) + (voff)[_i]), (PG8_LAS unsigned*)(lds + (bufoff) + ldsw + _i * 8192), 16, 0, 0); } while (0)
; #define PG8_LDA(dst, b, h) do { _Pragma("unroll") for (int m = 0; m < 4; ++m) _Pragma("unroll") for (int k = 0; k < 2; ++k) dst[m][k] = *(const PG8_LAS bf16x8*)(lds + PG8_SA(b, h) + aoff + m * 2048 + k * 1024); } while (0)
; #define PG8_LDB(dst, b, h) do { _Pragma("unroll") for (int n = 0; n < 2; ++n) _Pragma("unroll") for (int k = 0; k < 2; ++k) dst[n][k] = *(const PG8_LAS bf16x8*)(lds + PG8_SB(b, h) + boff + n * 2048 + k * 1024); } while (0)
; #define PG8_MMA(ai, bj, At, Bt) do { __builtin_amdgcn_s_setprio(1); _Pragma("unroll") for (int m = 0; m < 4; ++m) _Pragma("unroll") for (int n = 0; n < 2; ++n) _Pragma("unroll") for (int k = 0; k < 2; ++k) \
;         acc[ai][bj][m][n] = __builtin_amdgcn_mfma_f32_16x16x32_bf16(Bt[n][k], At[m][k], acc[ai][bj][m][n], 0, 0, 0); __builtin_amdgcn_s_setprio(0); } while (0)
; #define PG8_WAIT_V(n) asm volatile("s_waitcnt vmcnt(" #n ")" ::: "memory")
; #define PG8_WAIT_L(n) asm volatile("s_waitcnt lgkmcnt(" #n ")" ::: "memory")
; template <class Epi, class Sched, bool ALIGN_EPI = false, bool SP2 = false>
; __device__ __forceinline__ void gemm_phase(PG8_LAS unsigned char* lds, const Gemm g, const Sched& S, const Epi& E) {
;     ...
;             const bool last = (t == nt - 2);
;             const char* a1 = cA + (size_t)(t + 1) * kstep;
;             const char* a2 = last ? nA : cA + (size_t)(t + 2) * kstep; const char* b2 = last ? nB : cB + (size_t)(t + 2) * kstep;
;             const char* a3 = a2 + kstep; const char* b3 = b2 + kstep;
;             if (last && has_next) S.a_ready(nxt);
;             if constexpr (SP2) {
;             PG8_LDB(B0, 0, 0); PG8_LDB(B1, 0, 1); PG8_SCHED; PG8_LDA(At, 0, 0); PG8_STAGE(PG8_SA(1, 1), a1 + hstep, voffA);
;             PG8_WAIT_V(8); PG8_WAIT_L(0); PG8_BAR; PG8_MMA(0, 0, At, B0); PG8_MMA(0, 1, At, B1); PG8_BAR; PG8_SCHED;
;             PG8_LDA(At, 0, 1); PG8_STAGE(PG8_SB(0, 0), b2, voffB); PG8_STAGE(PG8_SB(0, 1), b2 + hstep, voffB); PG8_STAGE(PG8_SA(0, 0), a2, voffA);
;             PG8_WAIT_V(8); PG8_WAIT_L(0); PG8_BAR; PG8_MMA(1, 0, At, B0); PG8_MMA(1, 1, At, B1); PG8_BAR; PG8_SCHED;
.LBB0_808:
	s_add_u32 s28, s8, 0xfff80080
	s_addc_u32 s29, s9, -1
	s_add_i32 s48, 0, 0x10000
	s_cmp_eq_u32 s87, 28
	s_cselect_b32 s31, s23, s29
	s_cselect_b32 s30, s67, s28
	v_add_u32_e32 v160, s48, v163
	s_cselect_b32 s29, s21, s86
	s_cselect_b32 s28, s81, s83
	s_add_i32 s91, 0, 0x14000
	ds_read_b128 v[152:155], v160
	ds_read_b128 v[156:159], v160 offset:1024
	ds_read_b128 v[166:169], v160 offset:2048
	ds_read_b128 v[170:173], v160 offset:3072
	v_add_u32_e32 v160, s91, v163
	ds_read_b128 v[174:177], v160
	ds_read_b128 v[178:181], v160 offset:1024
	ds_read_b128 v[182:185], v160 offset:2048
	ds_read_b128 v[186:189], v160 offset:3072
	s_add_i32 m0, s13, 0xc000
	ds_read_b128 v[190:193], v165
	ds_read_b128 v[194:197], v165 offset:1024
	ds_read_b128 v[198:201], v165 offset:2048
	ds_read_b128 v[202:205], v165 offset:3072
	ds_read_b128 v[206:209], v165 offset:4096
	ds_read_b128 v[210:213], v165 offset:5120
	ds_read_b128 v[214:217], v165 offset:6144
	ds_read_b128 v[224:227], v165 offset:7168
	global_load_lds_dwordx4 v148, s[8:9]
	s_add_i32 m0, s13, 0xe000
	s_nop 0
	global_load_lds_dwordx4 v150, s[8:9]
	s_waitcnt vmcnt(8) lgkmcnt(0)
	s_barrier
	v_mfma_f32_16x16x32_bf16 v[144:147], v[152:155], v[190:193], v[144:147]
	v_mfma_f32_16x16x32_bf16 v[122:125], v[166:169], v[190:193], v[122:125]
	v_mfma_f32_16x16x32_bf16 v[110:113], v[152:155], v[198:201], v[110:113]
	v_mfma_f32_16x16x32_bf16 v[106:109], v[166:169], v[198:201], v[106:109]
	v_mfma_f32_16x16x32_bf16 v[94:97], v[152:155], v[206:209], v[94:97]
	v_mfma_f32_16x16x32_bf16 v[90:93], v[166:169], v[206:209], v[90:93]
	v_mfma_f32_16x16x32_bf16 v[78:81], v[152:155], v[214:217], v[78:81]
	v_mfma_f32_16x16x32_bf16 v[74:77], v[166:169], v[214:217], v[74:77]
	v_mfma_f32_16x16x32_bf16 v[144:147], v[156:159], v[194:197], v[144:147]
	v_mfma_f32_16x16x32_bf16 v[122:125], v[170:173], v[194:197], v[122:125]
	v_mfma_f32_16x16x32_bf16 v[110:113], v[156:159], v[202:205], v[110:113]
	v_mfma_f32_16x16x32_bf16 v[106:109], v[170:173], v[202:205], v[106:109]
	v_mfma_f32_16x16x32_bf16 v[94:97], v[156:159], v[210:213], v[94:97]
	v_mfma_f32_16x16x32_bf16 v[90:93], v[170:173], v[210:213], v[90:93]
	v_mfma_f32_16x16x32_bf16 v[78:81], v[156:159], v[224:227], v[78:81]
	v_mfma_f32_16x16x32_bf16 v[74:77], v[170:173], v[224:227], v[74:77]
	v_mfma_f32_16x16x32_bf16 v[118:121], v[174:177], v[190:193], v[118:121]
	v_mfma_f32_16x16x32_bf16 v[114:117], v[182:185], v[190:193], v[114:117]
	v_mfma_f32_16x16x32_bf16 v[102:105], v[174:177], v[198:201], v[102:105]
	v_mfma_f32_16x16x32_bf16 v[98:101], v[182:185], v[198:201], v[98:101]
	v_mfma_f32_16x16x32_bf16 v[86:89], v[174:177], v[206:209], v[86:89]
	v_mfma_f32_16x16x32_bf16 v[82:85], v[182:185], v[206:209], v[82:85]
	v_mfma_f32_16x16x32_bf16 v[70:73], v[174:177], v[214:217], v[70:73]
	v_mfma_f32_16x16x32_bf16 v[66:69], v[182:185], v[214:217], v[66:69]
	v_mfma_f32_16x16x32_bf16 v[118:121], v[178:181], v[194:197], v[118:121]
	v_mfma_f32_16x16x32_bf16 v[114:117], v[186:189], v[194:197], v[114:117]
	v_mfma_f32_16x16x32_bf16 v[102:105], v[178:181], v[202:205], v[102:105]
	v_mfma_f32_16x16x32_bf16 v[98:101], v[186:189], v[202:205], v[98:101]
	v_mfma_f32_16x16x32_bf16 v[86:89], v[178:181], v[210:213], v[86:89]
	v_mfma_f32_16x16x32_bf16 v[82:85], v[186:189], v[210:213], v[82:85]
	v_mfma_f32_16x16x32_bf16 v[70:73], v[178:181], v[224:227], v[70:73]
	v_mfma_f32_16x16x32_bf16 v[66:69], v[186:189], v[224:227], v[66:69]
	s_barrier
	s_add_i32 s48, s48, s12
	v_lshl_add_u64 v[160:161], s[28:29], 0, v[0:1]
	s_mov_b32 m0, s48
	ds_read_b128 v[190:193], v165 offset:16384
	ds_read_b128 v[194:197], v165 offset:17408
	ds_read_b128 v[198:201], v165 offset:18432
	ds_read_b128 v[202:205], v165 offset:19456
	ds_read_b128 v[206:209], v165 offset:20480
	ds_read_b128 v[210:213], v165 offset:21504
	ds_read_b128 v[214:217], v165 offset:22528
	ds_read_b128 v[224:227], v165 offset:23552
	global_load_lds_dwordx4 v[160:161], off
	s_add_i32 m0, s48, 0x2000
	s_add_u32 vcc_lo, s28, 0x80000
	v_lshl_add_u64 v[218:219], s[28:29], 0, v[126:127]
	s_addc_u32 vcc_hi, s29, 0
	s_add_i32 s48, s91, s12
	global_load_lds_dwordx4 v[218:219], off
	s_mov_b32 m0, s48
	v_lshl_add_u64 v[222:223], s[30:31], 0, v[126:127]
	global_load_lds_dwordx4 v0, vcc
	s_add_i32 m0, s48, 0x2000
	s_nop 0
	global_load_lds_dwordx4 v126, vcc
	s_mov_b32 m0, s13
	v_lshl_add_u64 v[220:221], s[30:31], 0, v[0:1]
	global_load_lds_dwordx4 v[220:221], off
	s_mov_b32 m0, s34
	s_nop 0
	global_load_lds_dwordx4 v[222:223], off
	s_waitcnt vmcnt(8) lgkmcnt(0)
	s_barrier
	v_mfma_f32_16x16x32_bf16 v[62:65], v[152:155], v[190:193], v[62:65]
	v_mfma_f32_16x16x32_bf16 v[58:61], v[166:169], v[190:193], v[58:61]
	v_mfma_f32_16x16x32_bf16 v[46:49], v[152:155], v[198:201], v[46:49]
	v_mfma_f32_16x16x32_bf16 v[42:45], v[166:169], v[198:201], v[42:45]
	v_mfma_f32_16x16x32_bf16 v[30:33], v[152:155], v[206:209], v[30:33]
	v_mfma_f32_16x16x32_bf16 v[26:29], v[166:169], v[206:209], v[26:29]
	v_mfma_f32_16x16x32_bf16 v[14:17], v[152:155], v[214:217], v[14:17]
	v_mfma_f32_16x16x32_bf16 v[10:13], v[166:169], v[214:217], v[10:13]
	v_mfma_f32_16x16x32_bf16 v[62:65], v[156:159], v[194:197], v[62:65]
	v_mfma_f32_16x16x32_bf16 v[58:61], v[170:173], v[194:197], v[58:61]
	v_mfma_f32_16x16x32_bf16 v[46:49], v[156:159], v[202:205], v[46:49]
	v_mfma_f32_16x16x32_bf16 v[42:45], v[170:173], v[202:205], v[42:45]
	v_mfma_f32_16x16x32_bf16 v[30:33], v[156:159], v[210:213], v[30:33]
	v_mfma_f32_16x16x32_bf16 v[26:29], v[170:173], v[210:213], v[26:29]
	v_mfma_f32_16x16x32_bf16 v[14:17], v[156:159], v[224:227], v[14:17]
	v_mfma_f32_16x16x32_bf16 v[10:13], v[170:173], v[224:227], v[10:13]
	v_mfma_f32_16x16x32_bf16 v[54:57], v[174:177], v[190:193], v[54:57]
	v_mfma_f32_16x16x32_bf16 v[50:53], v[182:185], v[190:193], v[50:53]
	v_mfma_f32_16x16x32_bf16 v[38:41], v[174:177], v[198:201], v[38:41]
	v_mfma_f32_16x16x32_bf16 v[34:37], v[182:185], v[198:201], v[34:37]
	v_mfma_f32_16x16x32_bf16 v[22:25], v[174:177], v[206:209], v[22:25]
	v_mfma_f32_16x16x32_bf16 v[18:21], v[182:185], v[206:209], v[18:21]
	v_mfma_f32_16x16x32_bf16 v[6:9], v[174:177], v[214:217], v[6:9]
	v_mfma_f32_16x16x32_bf16 v[2:5], v[182:185], v[214:217], v[2:5]
	v_mfma_f32_16x16x32_bf16 v[54:57], v[178:181], v[194:197], v[54:57]
	v_mfma_f32_16x16x32_bf16 v[50:53], v[186:189], v[194:197], v[50:53]
	v_mfma_f32_16x16x32_bf16 v[38:41], v[178:181], v[202:205], v[38:41]
	v_mfma_f32_16x16x32_bf16 v[34:37], v[186:189], v[202:205], v[34:37]
	v_mfma_f32_16x16x32_bf16 v[22:25], v[178:181], v[210:213], v[22:25]
	v_mfma_f32_16x16x32_bf16 v[18:21], v[186:189], v[210:213], v[18:21]
	v_mfma_f32_16x16x32_bf16 v[6:9], v[178:181], v[224:227], v[6:9]
	v_mfma_f32_16x16x32_bf16 v[2:5], v[186:189], v[224:227], v[2:5]
	s_barrier
; #define PG8_STAGE(bufoff, gbase, voff) do { _Pragma("unroll") for (int _i = 0; _i < 2; ++_i) \
;         __builtin_amdgcn_global_load_lds((const unsigned*)((const char*)(gbase) + (voff)[_i]), (PG8_LAS unsigned*)(lds + (bufoff) + ldsw + _i * 8192), 16, 0, 0); } while (0)
; #define PG8_LDA(dst, b, h) do { _Pragma("unroll") for (int m = 0; m < 4; ++m) _Pragma("unroll") for (int k = 0; k < 2; ++k) dst[m][k] = *(const PG8_LAS bf16x8*)(lds + PG8_SA(b, h) + aoff + m * 2048 + k * 1024); } while (0)
; #define PG8_LDB(dst, b, h) do { _Pragma("unroll") for (int n = 0; n < 2; ++n) _Pragma("unroll") for (int k = 0; k < 2; ++k) dst[n][k] = *(const PG8_LAS bf16x8*)(lds + PG8_SB(b, h) + boff + n * 2048 + k * 1024); } while (0)
; #define PG8_MMA(ai, bj, At, Bt) do { __builtin_amdgcn_s_setprio(1); _Pragma("unroll") for (int m = 0; m < 4; ++m) _Pragma("unroll") for (int n = 0; n < 2; ++n) _Pragma("unroll") for (int k = 0; k < 2; ++k) \
;         acc[ai][bj][m][n] = __builtin_amdgcn_mfma_f32_16x16x32_bf16(Bt[n][k], At[m][k], acc[ai][bj][m][n], 0, 0, 0); __builtin_amdgcn_s_setprio(0); } while (0)
; #define PG8_WAIT_V(n) asm volatile("s_waitcnt vmcnt(" #n ")" ::: "memory")
; #define PG8_WAIT_L(n) asm volatile("s_waitcnt lgkmcnt(" #n ")" ::: "memory")
; #define PG8_BAR __builtin_amdgcn_s_barrier()
; #define PG8_SCHED __builtin_amdgcn_sched_barrier(0)
; template <class Epi, class Sched, bool ALIGN_EPI = false, bool SP2 = false>
; __device__ __forceinline__ void gemm_phase(PG8_LAS unsigned char* lds, const Gemm g, const Sched& S, const Epi& E) {
;     ...
;             PG8_LDB(B0, 1, 0); PG8_LDB(B1, 1, 1); PG8_SCHED; PG8_LDA(At, 1, 0); PG8_STAGE(PG8_SA(0, 1), a2 + hstep, voffA);
;             PG8_WAIT_V(8); PG8_WAIT_L(0); PG8_BAR; PG8_MMA(0, 0, At, B0); PG8_MMA(0, 1, At, B1); PG8_BAR; PG8_SCHED;
;             PG8_LDA(At, 1, 1); PG8_STAGE(PG8_SB(1, 0), b3, voffB); PG8_STAGE(PG8_SB(1, 1), b3 + hstep, voffB); PG8_STAGE(PG8_SA(1, 0), a3, voffA);
;             PG8_WAIT_V(8); PG8_WAIT_L(0); PG8_BAR; PG8_MMA(1, 0, At, B0); PG8_MMA(1, 1, At, B1); PG8_BAR; PG8_SCHED;
	s_add_i32 s48, 0, 0x18000
	s_add_i32 s91, 0, 0x1c000
	v_add_u32_e32 v170, s48, v163
	v_add_u32_e32 v186, s91, v163
	ds_read_b128 v[152:155], v170
	ds_read_b128 v[156:159], v170 offset:1024
	ds_read_b128 v[166:169], v170 offset:2048
	ds_read_b128 v[170:173], v170 offset:3072
	ds_read_b128 v[174:177], v186
	ds_read_b128 v[178:181], v186 offset:1024
	ds_read_b128 v[182:185], v186 offset:2048
	ds_read_b128 v[186:189], v186 offset:3072
	s_add_u32 s30, s30, 0x80000
	s_addc_u32 s31, s31, 0
	s_mov_b32 m0, s35
	ds_read_b128 v[190:193], v165 offset:32768
	ds_read_b128 v[194:197], v165 offset:33792
	ds_read_b128 v[198:201], v165 offset:34816
	ds_read_b128 v[202:205], v165 offset:35840
	ds_read_b128 v[206:209], v165 offset:36864
	ds_read_b128 v[210:213], v165 offset:37888
	ds_read_b128 v[214:217], v165 offset:38912
	ds_read_b128 v[224:227], v165 offset:39936
	global_load_lds_dwordx4 v0, s[30:31]
	s_mov_b32 m0, s42
	s_nop 0
	global_load_lds_dwordx4 v126, s[30:31]
	s_waitcnt vmcnt(8) lgkmcnt(0)
	s_barrier
	v_mfma_f32_16x16x32_bf16 v[144:147], v[152:155], v[190:193], v[144:147]
	v_mfma_f32_16x16x32_bf16 v[122:125], v[166:169], v[190:193], v[122:125]
	v_mfma_f32_16x16x32_bf16 v[110:113], v[152:155], v[198:201], v[110:113]
	v_mfma_f32_16x16x32_bf16 v[106:109], v[166:169], v[198:201], v[106:109]
	v_mfma_f32_16x16x32_bf16 v[94:97], v[152:155], v[206:209], v[94:97]
	v_mfma_f32_16x16x32_bf16 v[90:93], v[166:169], v[206:209], v[90:93]
	v_mfma_f32_16x16x32_bf16 v[78:81], v[152:155], v[214:217], v[78:81]
	v_mfma_f32_16x16x32_bf16 v[74:77], v[166:169], v[214:217], v[74:77]
	v_mfma_f32_16x16x32_bf16 v[144:147], v[156:159], v[194:197], v[144:147]
	v_mfma_f32_16x16x32_bf16 v[122:125], v[170:173], v[194:197], v[122:125]
	v_mfma_f32_16x16x32_bf16 v[110:113], v[156:159], v[202:205], v[110:113]
	v_mfma_f32_16x16x32_bf16 v[106:109], v[170:173], v[202:205], v[106:109]
	v_mfma_f32_16x16x32_bf16 v[94:97], v[156:159], v[210:213], v[94:97]
	v_mfma_f32_16x16x32_bf16 v[90:93], v[170:173], v[210:213], v[90:93]
	v_mfma_f32_16x16x32_bf16 v[78:81], v[156:159], v[224:227], v[78:81]
	v_mfma_f32_16x16x32_bf16 v[74:77], v[170:173], v[224:227], v[74:77]
	v_mfma_f32_16x16x32_bf16 v[118:121], v[174:177], v[190:193], v[118:121]
	v_mfma_f32_16x16x32_bf16 v[114:117], v[182:185], v[190:193], v[114:117]
	v_mfma_f32_16x16x32_bf16 v[102:105], v[174:177], v[198:201], v[102:105]
	v_mfma_f32_16x16x32_bf16 v[98:101], v[182:185], v[198:201], v[98:101]
	v_mfma_f32_16x16x32_bf16 v[86:89], v[174:177], v[206:209], v[86:89]
	v_mfma_f32_16x16x32_bf16 v[82:85], v[182:185], v[206:209], v[82:85]
	v_mfma_f32_16x16x32_bf16 v[70:73], v[174:177], v[214:217], v[70:73]
	v_mfma_f32_16x16x32_bf16 v[66:69], v[182:185], v[214:217], v[66:69]
	v_mfma_f32_16x16x32_bf16 v[118:121], v[178:181], v[194:197], v[118:121]
	v_mfma_f32_16x16x32_bf16 v[114:117], v[186:189], v[194:197], v[114:117]
	v_mfma_f32_16x16x32_bf16 v[102:105], v[178:181], v[202:205], v[102:105]
	v_mfma_f32_16x16x32_bf16 v[98:101], v[186:189], v[202:205], v[98:101]
	v_mfma_f32_16x16x32_bf16 v[86:89], v[178:181], v[210:213], v[86:89]
	v_mfma_f32_16x16x32_bf16 v[82:85], v[186:189], v[210:213], v[82:85]
	v_mfma_f32_16x16x32_bf16 v[70:73], v[178:181], v[224:227], v[70:73]
	v_mfma_f32_16x16x32_bf16 v[66:69], v[186:189], v[224:227], v[66:69]
	s_barrier
	s_add_i32 s30, s48, s12
	v_lshl_add_u64 v[160:161], v[160:161], 0, s[64:65]
	s_mov_b32 m0, s30
	ds_read_b128 v[190:193], v165 offset:49152
	ds_read_b128 v[194:197], v165 offset:50176
	ds_read_b128 v[198:201], v165 offset:51200
	ds_read_b128 v[202:205], v165 offset:52224
	ds_read_b128 v[206:209], v165 offset:53248
	ds_read_b128 v[210:213], v165 offset:54272
	ds_read_b128 v[214:217], v165 offset:55296
	ds_read_b128 v[224:227], v165 offset:56320
	global_load_lds_dwordx4 v[160:161], off
	s_add_i32 m0, s30, 0x2000
	s_add_u32 s28, s28, 0x80080
	v_lshl_add_u64 v[160:161], v[218:219], 0, s[64:65]
	s_addc_u32 s29, s29, 0
	s_add_i32 s30, s91, s12
	global_load_lds_dwordx4 v[160:161], off
	s_mov_b32 m0, s30
	s_nop 0
	global_load_lds_dwordx4 v0, s[28:29]
	s_add_i32 m0, s30, 0x2000
	s_nop 0
	global_load_lds_dwordx4 v126, s[28:29]
	s_mov_b32 m0, s43
	v_lshl_add_u64 v[160:161], v[220:221], 0, s[64:65]
	global_load_lds_dwordx4 v[160:161], off
	s_mov_b32 m0, s76
	v_lshl_add_u64 v[160:161], v[222:223], 0, s[64:65]
	global_load_lds_dwordx4 v[160:161], off
	s_waitcnt vmcnt(8) lgkmcnt(0)
	s_barrier
	v_mfma_f32_16x16x32_bf16 v[62:65], v[152:155], v[190:193], v[62:65]
	v_mfma_f32_16x16x32_bf16 v[58:61], v[166:169], v[190:193], v[58:61]
	v_mfma_f32_16x16x32_bf16 v[46:49], v[152:155], v[198:201], v[46:49]
	v_mfma_f32_16x16x32_bf16 v[42:45], v[166:169], v[198:201], v[42:45]
	v_mfma_f32_16x16x32_bf16 v[30:33], v[152:155], v[206:209], v[30:33]
	v_mfma_f32_16x16x32_bf16 v[26:29], v[166:169], v[206:209], v[26:29]
	v_mfma_f32_16x16x32_bf16 v[14:17], v[152:155], v[214:217], v[14:17]
	v_mfma_f32_16x16x32_bf16 v[10:13], v[166:169], v[214:217], v[10:13]
	v_mfma_f32_16x16x32_bf16 v[62:65], v[156:159], v[194:197], v[62:65]
	v_mfma_f32_16x16x32_bf16 v[58:61], v[170:173], v[194:197], v[58:61]
	v_mfma_f32_16x16x32_bf16 v[46:49], v[156:159], v[202:205], v[46:49]
	v_mfma_f32_16x16x32_bf16 v[42:45], v[170:173], v[202:205], v[42:45]
	v_mfma_f32_16x16x32_bf16 v[30:33], v[156:159], v[210:213], v[30:33]
	v_mfma_f32_16x16x32_bf16 v[26:29], v[170:173], v[210:213], v[26:29]
	v_mfma_f32_16x16x32_bf16 v[14:17], v[156:159], v[224:227], v[14:17]
	v_mfma_f32_16x16x32_bf16 v[10:13], v[170:173], v[224:227], v[10:13]
	v_mfma_f32_16x16x32_bf16 v[54:57], v[174:177], v[190:193], v[54:57]
	v_mfma_f32_16x16x32_bf16 v[50:53], v[182:185], v[190:193], v[50:53]
	v_mfma_f32_16x16x32_bf16 v[38:41], v[174:177], v[198:201], v[38:41]
	v_mfma_f32_16x16x32_bf16 v[34:37], v[182:185], v[198:201], v[34:37]
	v_mfma_f32_16x16x32_bf16 v[22:25], v[174:177], v[206:209], v[22:25]
	v_mfma_f32_16x16x32_bf16 v[18:21], v[182:185], v[206:209], v[18:21]
	v_mfma_f32_16x16x32_bf16 v[6:9], v[174:177], v[214:217], v[6:9]
	v_mfma_f32_16x16x32_bf16 v[2:5], v[182:185], v[214:217], v[2:5]
	v_mfma_f32_16x16x32_bf16 v[54:57], v[178:181], v[194:197], v[54:57]
	v_mfma_f32_16x16x32_bf16 v[50:53], v[186:189], v[194:197], v[50:53]
	v_mfma_f32_16x16x32_bf16 v[38:41], v[178:181], v[202:205], v[38:41]
	v_mfma_f32_16x16x32_bf16 v[34:37], v[186:189], v[202:205], v[34:37]
	v_mfma_f32_16x16x32_bf16 v[22:25], v[178:181], v[210:213], v[22:25]
	v_mfma_f32_16x16x32_bf16 v[18:21], v[186:189], v[210:213], v[18:21]
	v_mfma_f32_16x16x32_bf16 v[6:9], v[178:181], v[224:227], v[6:9]
	v_mfma_f32_16x16x32_bf16 v[2:5], v[186:189], v[224:227], v[2:5]
	s_barrier
	s_add_i32 s87, s87, 2
	s_add_u32 s8, s8, 0x100
	s_addc_u32 s9, s9, 0
	s_add_u32 s83, s83, 0x100
	s_addc_u32 s86, s86, 0
	s_cmp_gt_u32 s87, 29
	s_cbranch_scc0 .LBB0_808
	s_and_b64 vcc, exec, s[18:19]
	s_cbranch_vccz .LBB0_811
	s_barrier

; #define PG8_STAGE(bufoff, gbase, voff) do { _Pragma("unroll") for (int _i = 0; _i < 2; ++_i) \
;         __builtin_amdgcn_global_load_lds((const unsigned*)((const char*)(gbase) + (voff)[_i]), (PG8_LAS unsigned*)(lds + (bufoff) + ldsw + _i * 8192), 16, 0, 0); } while (0)
; #define PG8_LDA(dst, b, h) do { _Pragma("unroll") for (int m = 0; m < 4; ++m) _Pragma("unroll") for (int k = 0; k < 2; ++k) dst[m][k] = *(const PG8_LAS bf16x8*)(lds + PG8_SA(b, h) + aoff + m * 2048 + k * 1024); } while (0)
; #define PG8_LDB(dst, b, h) do { _Pragma("unroll") for (int n = 0; n < 2; ++n) _Pragma("unroll") for (int k = 0; k < 2; ++k) dst[n][k] = *(const PG8_LAS bf16x8*)(lds + PG8_SB(b, h) + boff + n * 2048 + k * 1024); } while (0)
; #define PG8_MMA(ai, bj, At, Bt) do { __builtin_amdgcn_s_setprio(1); _Pragma("unroll") for (int m = 0; m < 4; ++m) _Pragma("unroll") for (int n = 0; n < 2; ++n) _Pragma("unroll") for (int k = 0; k < 2; ++k) \
;         acc[ai][bj][m][n] = __builtin_amdgcn_mfma_f32_16x16x32_bf16(Bt[n][k], At[m][k], acc[ai][bj][m][n], 0, 0, 0); __builtin_amdgcn_s_setprio(0); } while (0)
; #define PG8_WAIT_V(n) asm volatile("s_waitcnt vmcnt(" #n ")" ::: "memory")
; #define PG8_WAIT_L(n) asm volatile("s_waitcnt lgkmcnt(" #n ")" ::: "memory")
; template <class Epi, class Sched, bool ALIGN_EPI = false, bool SP2 = false>
; __device__ __forceinline__ void gemm_phase(PG8_LAS unsigned char* lds, const Gemm g, const Sched& S, const Epi& E) {
;     ...
;             const bool last = (t == nt - 2);
;             const char* a1 = cA + (size_t)(t + 1) * kstep;
;             const char* a2 = last ? nA : cA + (size_t)(t + 2) * kstep; const char* b2 = last ? nB : cB + (size_t)(t + 2) * kstep;
;             const char* a3 = a2 + kstep; const char* b3 = b2 + kstep;
;             if (last && has_next) S.a_ready(nxt);
;             if constexpr (SP2) {
;             PG8_LDB(B0, 0, 0); PG8_LDB(B1, 0, 1); PG8_SCHED; PG8_LDA(At, 0, 0); PG8_STAGE(PG8_SA(1, 1), a1 + hstep, voffA);
;             PG8_WAIT_V(8); PG8_WAIT_L(0); PG8_BAR; PG8_MMA(0, 0, At, B0); PG8_MMA(0, 1, At, B1); PG8_BAR; PG8_SCHED;
;             PG8_LDA(At, 0, 1); PG8_STAGE(PG8_SB(0, 0), b2, voffB); PG8_STAGE(PG8_SB(0, 1), b2 + hstep, voffB); PG8_STAGE(PG8_SA(0, 0), a2, voffA);
;             PG8_WAIT_V(8); PG8_WAIT_L(0); PG8_BAR; PG8_MMA(1, 0, At, B0); PG8_MMA(1, 1, At, B1); PG8_BAR; PG8_SCHED;
.LBB0_910:
	s_add_u32 s28, s0, 0xfff80080
	s_addc_u32 s29, s1, -1
	s_add_i32 s48, 0, 0x10000
	s_cmp_eq_u32 s81, 28
	s_cselect_b32 s31, s21, s29
	s_cselect_b32 s30, s35, s28
	s_cselect_b32 s29, s23, s67
	s_cselect_b32 s28, s40, s41
	s_add_i32 s91, 0, 0x14000
	v_add_u32_e32 v164, s48, v179
	v_add_u32_e32 v176, s91, v179
	ds_read_b128 v[152:155], v164
	ds_read_b128 v[156:159], v164 offset:1024
	ds_read_b128 v[160:163], v164 offset:2048
	ds_read_b128 v[164:167], v164 offset:3072
	ds_read_b128 v[168:171], v176
	ds_read_b128 v[172:175], v176 offset:1024
	ds_read_b128 v[182:185], v176 offset:2048
	ds_read_b128 v[186:189], v176 offset:3072
	s_add_i32 m0, s43, 0xc000
	ds_read_b128 v[190:193], v181
	ds_read_b128 v[194:197], v181 offset:1024
	ds_read_b128 v[198:201], v181 offset:2048
	ds_read_b128 v[202:205], v181 offset:3072
	ds_read_b128 v[206:209], v181 offset:4096
	ds_read_b128 v[210:213], v181 offset:5120
	ds_read_b128 v[214:217], v181 offset:6144
	ds_read_b128 v[224:227], v181 offset:7168
	global_load_lds_dwordx4 v148, s[0:1]
	s_add_i32 m0, s43, 0xe000
	s_nop 0
	global_load_lds_dwordx4 v150, s[0:1]
	s_waitcnt vmcnt(8) lgkmcnt(0)
	s_barrier
	v_mfma_f32_16x16x32_bf16 v[74:77], v[152:155], v[190:193], v[74:77]
	v_mfma_f32_16x16x32_bf16 v[78:81], v[160:163], v[190:193], v[78:81]
	v_mfma_f32_16x16x32_bf16 v[102:105], v[152:155], v[198:201], v[102:105]
	v_mfma_f32_16x16x32_bf16 v[106:109], v[160:163], v[198:201], v[106:109]
	v_mfma_f32_16x16x32_bf16 v[122:125], v[152:155], v[206:209], v[122:125]
	v_mfma_f32_16x16x32_bf16 v[144:147], v[160:163], v[206:209], v[144:147]
	v_mfma_f32_16x16x32_bf16 v[90:93], v[152:155], v[214:217], v[90:93]
	v_mfma_f32_16x16x32_bf16 v[86:89], v[160:163], v[214:217], v[86:89]
	v_mfma_f32_16x16x32_bf16 v[74:77], v[156:159], v[194:197], v[74:77]
	v_mfma_f32_16x16x32_bf16 v[78:81], v[164:167], v[194:197], v[78:81]
	v_mfma_f32_16x16x32_bf16 v[102:105], v[156:159], v[202:205], v[102:105]
	v_mfma_f32_16x16x32_bf16 v[106:109], v[164:167], v[202:205], v[106:109]
	v_mfma_f32_16x16x32_bf16 v[122:125], v[156:159], v[210:213], v[122:125]
	v_mfma_f32_16x16x32_bf16 v[144:147], v[164:167], v[210:213], v[144:147]
	v_mfma_f32_16x16x32_bf16 v[90:93], v[156:159], v[224:227], v[90:93]
	v_mfma_f32_16x16x32_bf16 v[86:89], v[164:167], v[224:227], v[86:89]
	v_mfma_f32_16x16x32_bf16 v[82:85], v[168:171], v[190:193], v[82:85]
	v_mfma_f32_16x16x32_bf16 v[94:97], v[182:185], v[190:193], v[94:97]
	v_mfma_f32_16x16x32_bf16 v[110:113], v[168:171], v[198:201], v[110:113]
	v_mfma_f32_16x16x32_bf16 v[118:121], v[182:185], v[198:201], v[118:121]
	v_mfma_f32_16x16x32_bf16 v[114:117], v[168:171], v[206:209], v[114:117]
	v_mfma_f32_16x16x32_bf16 v[98:101], v[182:185], v[206:209], v[98:101]
	v_mfma_f32_16x16x32_bf16 v[70:73], v[168:171], v[214:217], v[70:73]
	v_mfma_f32_16x16x32_bf16 v[66:69], v[182:185], v[214:217], v[66:69]
	v_mfma_f32_16x16x32_bf16 v[82:85], v[172:175], v[194:197], v[82:85]
	v_mfma_f32_16x16x32_bf16 v[94:97], v[186:189], v[194:197], v[94:97]
	v_mfma_f32_16x16x32_bf16 v[110:113], v[172:175], v[202:205], v[110:113]
	v_mfma_f32_16x16x32_bf16 v[118:121], v[186:189], v[202:205], v[118:121]
	v_mfma_f32_16x16x32_bf16 v[114:117], v[172:175], v[210:213], v[114:117]
	v_mfma_f32_16x16x32_bf16 v[98:101], v[186:189], v[210:213], v[98:101]
	v_mfma_f32_16x16x32_bf16 v[70:73], v[172:175], v[224:227], v[70:73]
	v_mfma_f32_16x16x32_bf16 v[66:69], v[186:189], v[224:227], v[66:69]
	s_barrier
	s_add_i32 s48, s48, s42
	v_lshl_add_u64 v[176:177], s[28:29], 0, v[0:1]
	s_mov_b32 m0, s48
	ds_read_b128 v[190:193], v181 offset:16384
	ds_read_b128 v[194:197], v181 offset:17408
	ds_read_b128 v[198:201], v181 offset:18432
	ds_read_b128 v[202:205], v181 offset:19456
	ds_read_b128 v[206:209], v181 offset:20480
	ds_read_b128 v[210:213], v181 offset:21504
	ds_read_b128 v[214:217], v181 offset:22528
	ds_read_b128 v[224:227], v181 offset:23552
	global_load_lds_dwordx4 v[176:177], off
	s_add_i32 m0, s48, 0x2000
	s_add_u32 vcc_lo, s28, 0x80000
	v_lshl_add_u64 v[218:219], s[28:29], 0, v[126:127]
	s_addc_u32 vcc_hi, s29, 0
	s_add_i32 s48, s91, s42
	global_load_lds_dwordx4 v[218:219], off
	s_mov_b32 m0, s48
	v_lshl_add_u64 v[222:223], s[30:31], 0, v[126:127]
	global_load_lds_dwordx4 v0, vcc
	s_add_i32 m0, s48, 0x2000
	s_nop 0
	global_load_lds_dwordx4 v126, vcc
	s_mov_b32 m0, s43
	v_lshl_add_u64 v[220:221], s[30:31], 0, v[0:1]
	global_load_lds_dwordx4 v[220:221], off
	s_mov_b32 m0, s76
	s_nop 0
	global_load_lds_dwordx4 v[222:223], off
	s_waitcnt vmcnt(8) lgkmcnt(0)
	s_barrier
	v_mfma_f32_16x16x32_bf16 v[62:65], v[152:155], v[190:193], v[62:65]
	v_mfma_f32_16x16x32_bf16 v[58:61], v[160:163], v[190:193], v[58:61]
	v_mfma_f32_16x16x32_bf16 v[46:49], v[152:155], v[198:201], v[46:49]
	v_mfma_f32_16x16x32_bf16 v[42:45], v[160:163], v[198:201], v[42:45]
	v_mfma_f32_16x16x32_bf16 v[30:33], v[152:155], v[206:209], v[30:33]
	v_mfma_f32_16x16x32_bf16 v[26:29], v[160:163], v[206:209], v[26:29]
	v_mfma_f32_16x16x32_bf16 v[14:17], v[152:155], v[214:217], v[14:17]
	v_mfma_f32_16x16x32_bf16 v[10:13], v[160:163], v[214:217], v[10:13]
	v_mfma_f32_16x16x32_bf16 v[62:65], v[156:159], v[194:197], v[62:65]
	v_mfma_f32_16x16x32_bf16 v[58:61], v[164:167], v[194:197], v[58:61]
	v_mfma_f32_16x16x32_bf16 v[46:49], v[156:159], v[202:205], v[46:49]
	v_mfma_f32_16x16x32_bf16 v[42:45], v[164:167], v[202:205], v[42:45]
	v_mfma_f32_16x16x32_bf16 v[30:33], v[156:159], v[210:213], v[30:33]
	v_mfma_f32_16x16x32_bf16 v[26:29], v[164:167], v[210:213], v[26:29]
	v_mfma_f32_16x16x32_bf16 v[14:17], v[156:159], v[224:227], v[14:17]
	v_mfma_f32_16x16x32_bf16 v[10:13], v[164:167], v[224:227], v[10:13]
	v_mfma_f32_16x16x32_bf16 v[54:57], v[168:171], v[190:193], v[54:57]
	v_mfma_f32_16x16x32_bf16 v[50:53], v[182:185], v[190:193], v[50:53]
	v_mfma_f32_16x16x32_bf16 v[38:41], v[168:171], v[198:201], v[38:41]
	v_mfma_f32_16x16x32_bf16 v[34:37], v[182:185], v[198:201], v[34:37]
	v_mfma_f32_16x16x32_bf16 v[22:25], v[168:171], v[206:209], v[22:25]
	v_mfma_f32_16x16x32_bf16 v[18:21], v[182:185], v[206:209], v[18:21]
	v_mfma_f32_16x16x32_bf16 v[6:9], v[168:171], v[214:217], v[6:9]
	v_mfma_f32_16x16x32_bf16 v[2:5], v[182:185], v[214:217], v[2:5]
	v_mfma_f32_16x16x32_bf16 v[54:57], v[172:175], v[194:197], v[54:57]
	v_mfma_f32_16x16x32_bf16 v[50:53], v[186:189], v[194:197], v[50:53]
	v_mfma_f32_16x16x32_bf16 v[38:41], v[172:175], v[202:205], v[38:41]
	v_mfma_f32_16x16x32_bf16 v[34:37], v[186:189], v[202:205], v[34:37]
	v_mfma_f32_16x16x32_bf16 v[22:25], v[172:175], v[210:213], v[22:25]
	v_mfma_f32_16x16x32_bf16 v[18:21], v[186:189], v[210:213], v[18:21]
	v_mfma_f32_16x16x32_bf16 v[6:9], v[172:175], v[224:227], v[6:9]
	v_mfma_f32_16x16x32_bf16 v[2:5], v[186:189], v[224:227], v[2:5]
	s_barrier
; #define PG8_STAGE(bufoff, gbase, voff) do { _Pragma("unroll") for (int _i = 0; _i < 2; ++_i) \
;         __builtin_amdgcn_global_load_lds((const unsigned*)((const char*)(gbase) + (voff)[_i]), (PG8_LAS unsigned*)(lds + (bufoff) + ldsw + _i * 8192), 16, 0, 0); } while (0)
; #define PG8_LDA(dst, b, h) do { _Pragma("unroll") for (int m = 0; m < 4; ++m) _Pragma("unroll") for (int k = 0; k < 2; ++k) dst[m][k] = *(const PG8_LAS bf16x8*)(lds + PG8_SA(b, h) + aoff + m * 2048 + k * 1024); } while (0)
; #define PG8_LDB(dst, b, h) do { _Pragma("unroll") for (int n = 0; n < 2; ++n) _Pragma("unroll") for (int k = 0; k < 2; ++k) dst[n][k] = *(const PG8_LAS bf16x8*)(lds + PG8_SB(b, h) + boff + n * 2048 + k * 1024); } while (0)
; #define PG8_MMA(ai, bj, At, Bt) do { __builtin_amdgcn_s_setprio(1); _Pragma("unroll") for (int m = 0; m < 4; ++m) _Pragma("unroll") for (int n = 0; n < 2; ++n) _Pragma("unroll") for (int k = 0; k < 2; ++k) \
;         acc[ai][bj][m][n] = __builtin_amdgcn_mfma_f32_16x16x32_bf16(Bt[n][k], At[m][k], acc[ai][bj][m][n], 0, 0, 0); __builtin_amdgcn_s_setprio(0); } while (0)
; #define PG8_WAIT_V(n) asm volatile("s_waitcnt vmcnt(" #n ")" ::: "memory")
; #define PG8_WAIT_L(n) asm volatile("s_waitcnt lgkmcnt(" #n ")" ::: "memory")
; #define PG8_BAR __builtin_amdgcn_s_barrier()
; #define PG8_SCHED __builtin_amdgcn_sched_barrier(0)
; template <class Epi, class Sched, bool ALIGN_EPI = false, bool SP2 = false>
; __device__ __forceinline__ void gemm_phase(PG8_LAS unsigned char* lds, const Gemm g, const Sched& S, const Epi& E) {
;     ...
;             PG8_LDB(B0, 1, 0); PG8_LDB(B1, 1, 1); PG8_SCHED; PG8_LDA(At, 1, 0); PG8_STAGE(PG8_SA(0, 1), a2 + hstep, voffA);
;             PG8_WAIT_V(8); PG8_WAIT_L(0); PG8_BAR; PG8_MMA(0, 0, At, B0); PG8_MMA(0, 1, At, B1); PG8_BAR; PG8_SCHED;
;             PG8_LDA(At, 1, 1); PG8_STAGE(PG8_SB(1, 0), b3, voffB); PG8_STAGE(PG8_SB(1, 1), b3 + hstep, voffB); PG8_STAGE(PG8_SA(1, 0), a3, voffA);
;             PG8_WAIT_V(8); PG8_WAIT_L(0); PG8_BAR; PG8_MMA(1, 0, At, B0); PG8_MMA(1, 1, At, B1); PG8_BAR; PG8_SCHED;
	s_add_i32 s48, 0, 0x18000
	s_add_i32 s91, 0, 0x1c000
	v_add_u32_e32 v164, s48, v179
	v_add_u32_e32 v186, s91, v179
	ds_read_b128 v[152:155], v164
	ds_read_b128 v[156:159], v164 offset:1024
	ds_read_b128 v[160:163], v164 offset:2048
	ds_read_b128 v[164:167], v164 offset:3072
	ds_read_b128 v[168:171], v186
	ds_read_b128 v[172:175], v186 offset:1024
	ds_read_b128 v[182:185], v186 offset:2048
	ds_read_b128 v[186:189], v186 offset:3072
	s_add_u32 s30, s30, 0x80000
	s_addc_u32 s31, s31, 0
	s_mov_b32 m0, s82
	ds_read_b128 v[190:193], v181 offset:32768
	ds_read_b128 v[194:197], v181 offset:33792
	ds_read_b128 v[198:201], v181 offset:34816
	ds_read_b128 v[202:205], v181 offset:35840
	ds_read_b128 v[206:209], v181 offset:36864
	ds_read_b128 v[210:213], v181 offset:37888
	ds_read_b128 v[214:217], v181 offset:38912
	ds_read_b128 v[224:227], v181 offset:39936
	global_load_lds_dwordx4 v0, s[30:31]
	s_mov_b32 m0, s83
	s_nop 0
	global_load_lds_dwordx4 v126, s[30:31]
	s_waitcnt vmcnt(8) lgkmcnt(0)
	s_barrier
	v_mfma_f32_16x16x32_bf16 v[74:77], v[152:155], v[190:193], v[74:77]
	v_mfma_f32_16x16x32_bf16 v[78:81], v[160:163], v[190:193], v[78:81]
	v_mfma_f32_16x16x32_bf16 v[102:105], v[152:155], v[198:201], v[102:105]
	v_mfma_f32_16x16x32_bf16 v[106:109], v[160:163], v[198:201], v[106:109]
	v_mfma_f32_16x16x32_bf16 v[122:125], v[152:155], v[206:209], v[122:125]
	v_mfma_f32_16x16x32_bf16 v[144:147], v[160:163], v[206:209], v[144:147]
	v_mfma_f32_16x16x32_bf16 v[90:93], v[152:155], v[214:217], v[90:93]
	v_mfma_f32_16x16x32_bf16 v[86:89], v[160:163], v[214:217], v[86:89]
	v_mfma_f32_16x16x32_bf16 v[74:77], v[156:159], v[194:197], v[74:77]
	v_mfma_f32_16x16x32_bf16 v[78:81], v[164:167], v[194:197], v[78:81]
	v_mfma_f32_16x16x32_bf16 v[102:105], v[156:159], v[202:205], v[102:105]
	v_mfma_f32_16x16x32_bf16 v[106:109], v[164:167], v[202:205], v[106:109]
	v_mfma_f32_16x16x32_bf16 v[122:125], v[156:159], v[210:213], v[122:125]
	v_mfma_f32_16x16x32_bf16 v[144:147], v[164:167], v[210:213], v[144:147]
	v_mfma_f32_16x16x32_bf16 v[90:93], v[156:159], v[224:227], v[90:93]
	v_mfma_f32_16x16x32_bf16 v[86:89], v[164:167], v[224:227], v[86:89]
	v_mfma_f32_16x16x32_bf16 v[82:85], v[168:171], v[190:193], v[82:85]
	v_mfma_f32_16x16x32_bf16 v[94:97], v[182:185], v[190:193], v[94:97]
	v_mfma_f32_16x16x32_bf16 v[110:113], v[168:171], v[198:201], v[110:113]
	v_mfma_f32_16x16x32_bf16 v[118:121], v[182:185], v[198:201], v[118:121]
	v_mfma_f32_16x16x32_bf16 v[114:117], v[168:171], v[206:209], v[114:117]
	v_mfma_f32_16x16x32_bf16 v[98:101], v[182:185], v[206:209], v[98:101]
	v_mfma_f32_16x16x32_bf16 v[70:73], v[168:171], v[214:217], v[70:73]
	v_mfma_f32_16x16x32_bf16 v[66:69], v[182:185], v[214:217], v[66:69]
	v_mfma_f32_16x16x32_bf16 v[82:85], v[172:175], v[194:197], v[82:85]
	v_mfma_f32_16x16x32_bf16 v[94:97], v[186:189], v[194:197], v[94:97]
	v_mfma_f32_16x16x32_bf16 v[110:113], v[172:175], v[202:205], v[110:113]
	v_mfma_f32_16x16x32_bf16 v[118:121], v[186:189], v[202:205], v[118:121]
	v_mfma_f32_16x16x32_bf16 v[114:117], v[172:175], v[210:213], v[114:117]
	v_mfma_f32_16x16x32_bf16 v[98:101], v[186:189], v[210:213], v[98:101]
	v_mfma_f32_16x16x32_bf16 v[70:73], v[172:175], v[224:227], v[70:73]
	v_mfma_f32_16x16x32_bf16 v[66:69], v[186:189], v[224:227], v[66:69]
	s_barrier
	s_add_i32 s30, s48, s42
	v_lshl_add_u64 v[176:177], v[176:177], 0, s[64:65]
	s_mov_b32 m0, s30
	ds_read_b128 v[190:193], v181 offset:49152
	ds_read_b128 v[194:197], v181 offset:50176
	ds_read_b128 v[198:201], v181 offset:51200
	ds_read_b128 v[202:205], v181 offset:52224
	ds_read_b128 v[206:209], v181 offset:53248
	ds_read_b128 v[210:213], v181 offset:54272
	ds_read_b128 v[214:217], v181 offset:55296
	ds_read_b128 v[224:227], v181 offset:56320
	global_load_lds_dwordx4 v[176:177], off
	s_add_i32 m0, s30, 0x2000
	s_add_u32 s28, s28, 0x80080
	v_lshl_add_u64 v[176:177], v[218:219], 0, s[64:65]
	s_addc_u32 s29, s29, 0
	s_add_i32 s30, s91, s42
	global_load_lds_dwordx4 v[176:177], off
	s_mov_b32 m0, s30
	s_nop 0
	global_load_lds_dwordx4 v0, s[28:29]
	s_add_i32 m0, s30, 0x2000
	s_nop 0
	global_load_lds_dwordx4 v126, s[28:29]
	s_mov_b32 m0, s86
	v_lshl_add_u64 v[176:177], v[220:221], 0, s[64:65]
	global_load_lds_dwordx4 v[176:177], off
	s_mov_b32 m0, s87
	v_lshl_add_u64 v[176:177], v[222:223], 0, s[64:65]
	global_load_lds_dwordx4 v[176:177], off
	s_waitcnt vmcnt(8) lgkmcnt(0)
	s_barrier
	v_mfma_f32_16x16x32_bf16 v[62:65], v[152:155], v[190:193], v[62:65]
	v_mfma_f32_16x16x32_bf16 v[58:61], v[160:163], v[190:193], v[58:61]
	v_mfma_f32_16x16x32_bf16 v[46:49], v[152:155], v[198:201], v[46:49]
	v_mfma_f32_16x16x32_bf16 v[42:45], v[160:163], v[198:201], v[42:45]
	v_mfma_f32_16x16x32_bf16 v[30:33], v[152:155], v[206:209], v[30:33]
	v_mfma_f32_16x16x32_bf16 v[26:29], v[160:163], v[206:209], v[26:29]
	v_mfma_f32_16x16x32_bf16 v[14:17], v[152:155], v[214:217], v[14:17]
	v_mfma_f32_16x16x32_bf16 v[10:13], v[160:163], v[214:217], v[10:13]
	v_mfma_f32_16x16x32_bf16 v[62:65], v[156:159], v[194:197], v[62:65]
	v_mfma_f32_16x16x32_bf16 v[58:61], v[164:167], v[194:197], v[58:61]
	v_mfma_f32_16x16x32_bf16 v[46:49], v[156:159], v[202:205], v[46:49]
	v_mfma_f32_16x16x32_bf16 v[42:45], v[164:167], v[202:205], v[42:45]
	v_mfma_f32_16x16x32_bf16 v[30:33], v[156:159], v[210:213], v[30:33]
	v_mfma_f32_16x16x32_bf16 v[26:29], v[164:167], v[210:213], v[26:29]
	v_mfma_f32_16x16x32_bf16 v[14:17], v[156:159], v[224:227], v[14:17]
	v_mfma_f32_16x16x32_bf16 v[10:13], v[164:167], v[224:227], v[10:13]
	v_mfma_f32_16x16x32_bf16 v[54:57], v[168:171], v[190:193], v[54:57]
	v_mfma_f32_16x16x32_bf16 v[50:53], v[182:185], v[190:193], v[50:53]
	v_mfma_f32_16x16x32_bf16 v[38:41], v[168:171], v[198:201], v[38:41]
	v_mfma_f32_16x16x32_bf16 v[34:37], v[182:185], v[198:201], v[34:37]
	v_mfma_f32_16x16x32_bf16 v[22:25], v[168:171], v[206:209], v[22:25]
	v_mfma_f32_16x16x32_bf16 v[18:21], v[182:185], v[206:209], v[18:21]
	v_mfma_f32_16x16x32_bf16 v[6:9], v[168:171], v[214:217], v[6:9]
	v_mfma_f32_16x16x32_bf16 v[2:5], v[182:185], v[214:217], v[2:5]
	v_mfma_f32_16x16x32_bf16 v[54:57], v[172:175], v[194:197], v[54:57]
	v_mfma_f32_16x16x32_bf16 v[50:53], v[186:189], v[194:197], v[50:53]
	v_mfma_f32_16x16x32_bf16 v[38:41], v[172:175], v[202:205], v[38:41]
	v_mfma_f32_16x16x32_bf16 v[34:37], v[186:189], v[202:205], v[34:37]
	v_mfma_f32_16x16x32_bf16 v[22:25], v[172:175], v[210:213], v[22:25]
	v_mfma_f32_16x16x32_bf16 v[18:21], v[186:189], v[210:213], v[18:21]
	v_mfma_f32_16x16x32_bf16 v[6:9], v[172:175], v[224:227], v[6:9]
	v_mfma_f32_16x16x32_bf16 v[2:5], v[186:189], v[224:227], v[2:5]
	s_barrier
	s_add_i32 s81, s81, 2
	s_add_u32 s0, s0, 0x100
	s_addc_u32 s1, s1, 0
	s_add_u32 s41, s41, 0x100
	s_addc_u32 s67, s67, 0
	s_cmp_gt_u32 s81, 29
	s_cbranch_scc0 .LBB0_910
	s_and_b64 vcc, exec, s[18:19]
	s_cbranch_vccz .LBB0_913
	s_barrier

; #define PG8_STAGE(bufoff, gbase, voff) do { _Pragma("unroll") for (int _i = 0; _i < 2; ++_i) \
;         __builtin_amdgcn_global_load_lds((const unsigned*)((const char*)(gbase) + (voff)[_i]), (PG8_LAS unsigned*)(lds + (bufoff) + ldsw + _i * 8192), 16, 0, 0); } while (0)
; #define PG8_LDA(dst, b, h) do { _Pragma("unroll") for (int m = 0; m < 4; ++m) _Pragma("unroll") for (int k = 0; k < 2; ++k) dst[m][k] = *(const PG8_LAS bf16x8*)(lds + PG8_SA(b, h) + aoff + m * 2048 + k * 1024); } while (0)
; #define PG8_LDB(dst, b, h) do { _Pragma("unroll") for (int n = 0; n < 2; ++n) _Pragma("unroll") for (int k = 0; k < 2; ++k) dst[n][k] = *(const PG8_LAS bf16x8*)(lds + PG8_SB(b, h) + boff + n * 2048 + k * 1024); } while (0)
; #define PG8_MMA(ai, bj, At, Bt) do { __builtin_amdgcn_s_setprio(1); _Pragma("unroll") for (int m = 0; m < 4; ++m) _Pragma("unroll") for (int n = 0; n < 2; ++n) _Pragma("unroll") for (int k = 0; k < 2; ++k) \
;         acc[ai][bj][m][n] = __builtin_amdgcn_mfma_f32_16x16x32_bf16(Bt[n][k], At[m][k], acc[ai][bj][m][n], 0, 0, 0); __builtin_amdgcn_s_setprio(0); } while (0)
; #define PG8_WAIT_V(n) asm volatile("s_waitcnt vmcnt(" #n ")" ::: "memory")
; #define PG8_WAIT_L(n) asm volatile("s_waitcnt lgkmcnt(" #n ")" ::: "memory")
; template <class Epi, class Sched, bool ALIGN_EPI = false, bool SP2 = false>
; __device__ __forceinline__ void gemm_phase(PG8_LAS unsigned char* lds, const Gemm g, const Sched& S, const Epi& E) {
;     ...
;             const bool last = (t == nt - 2);
;             const char* a1 = cA + (size_t)(t + 1) * kstep;
;             const char* a2 = last ? nA : cA + (size_t)(t + 2) * kstep; const char* b2 = last ? nB : cB + (size_t)(t + 2) * kstep;
;             const char* a3 = a2 + kstep; const char* b3 = b2 + kstep;
;             if (last && has_next) S.a_ready(nxt);
;             if constexpr (SP2) {
;             PG8_LDB(B0, 0, 0); PG8_LDB(B1, 0, 1); PG8_SCHED; PG8_LDA(At, 0, 0); PG8_STAGE(PG8_SA(1, 1), a1 + hstep, voffA);
;             PG8_WAIT_V(8); PG8_WAIT_L(0); PG8_BAR; PG8_MMA(0, 0, At, B0); PG8_MMA(0, 1, At, B1); PG8_BAR; PG8_SCHED;
;             PG8_LDA(At, 0, 1); PG8_STAGE(PG8_SB(0, 0), b2, voffB); PG8_STAGE(PG8_SB(0, 1), b2 + hstep, voffB); PG8_STAGE(PG8_SA(0, 0), a2, voffA);
;             PG8_WAIT_V(8); PG8_WAIT_L(0); PG8_BAR; PG8_MMA(1, 0, At, B0); PG8_MMA(1, 1, At, B1); PG8_BAR; PG8_SCHED;
.LBB0_963:
	s_add_u32 s24, s0, 0xfff80080
	s_addc_u32 s25, s1, -1
	s_add_i32 s43, 0, 0x10000
	s_cmp_eq_u32 s42, 28
	s_cselect_b32 s27, s13, s25
	s_cselect_b32 s26, s17, s24
	s_cselect_b32 s25, s19, s41
	s_cselect_b32 s24, s29, s40
	s_add_i32 s48, 0, 0x14000
	v_add_u32_e32 v164, s43, v197
	v_add_u32_e32 v180, s48, v197
	ds_read_b128 v[152:155], v164
	ds_read_b128 v[156:159], v164 offset:1024
	ds_read_b128 v[160:163], v164 offset:2048
	ds_read_b128 v[164:167], v164 offset:3072
	ds_read_b128 v[168:171], v180
	ds_read_b128 v[172:175], v180 offset:1024
	ds_read_b128 v[176:179], v180 offset:2048
	ds_read_b128 v[180:183], v180 offset:3072
	s_add_i32 m0, s31, 0xc000
	ds_read_b128 v[184:187], v199
	ds_read_b128 v[188:191], v199 offset:1024
	ds_read_b128 v[192:195], v199 offset:2048
	ds_read_b128 v[200:203], v199 offset:3072
	ds_read_b128 v[204:207], v199 offset:4096
	ds_read_b128 v[208:211], v199 offset:5120
	ds_read_b128 v[212:215], v199 offset:6144
	ds_read_b128 v[216:219], v199 offset:7168
	global_load_lds_dwordx4 v148, s[0:1]
	s_add_i32 m0, s31, 0xe000
	s_nop 0
	global_load_lds_dwordx4 v150, s[0:1]
	s_waitcnt vmcnt(8) lgkmcnt(0)
	s_barrier
	v_mfma_f32_16x16x32_bf16 v[144:147], v[152:155], v[184:187], v[144:147]
	v_mfma_f32_16x16x32_bf16 v[122:125], v[160:163], v[184:187], v[122:125]
	v_mfma_f32_16x16x32_bf16 v[110:113], v[152:155], v[192:195], v[110:113]
	v_mfma_f32_16x16x32_bf16 v[106:109], v[160:163], v[192:195], v[106:109]
	v_mfma_f32_16x16x32_bf16 v[94:97], v[152:155], v[204:207], v[94:97]
	v_mfma_f32_16x16x32_bf16 v[90:93], v[160:163], v[204:207], v[90:93]
	v_mfma_f32_16x16x32_bf16 v[78:81], v[152:155], v[212:215], v[78:81]
	v_mfma_f32_16x16x32_bf16 v[74:77], v[160:163], v[212:215], v[74:77]
	v_mfma_f32_16x16x32_bf16 v[144:147], v[156:159], v[188:191], v[144:147]
	v_mfma_f32_16x16x32_bf16 v[122:125], v[164:167], v[188:191], v[122:125]
	v_mfma_f32_16x16x32_bf16 v[110:113], v[156:159], v[200:203], v[110:113]
	v_mfma_f32_16x16x32_bf16 v[106:109], v[164:167], v[200:203], v[106:109]
	v_mfma_f32_16x16x32_bf16 v[94:97], v[156:159], v[208:211], v[94:97]
	v_mfma_f32_16x16x32_bf16 v[90:93], v[164:167], v[208:211], v[90:93]
	v_mfma_f32_16x16x32_bf16 v[78:81], v[156:159], v[216:219], v[78:81]
	v_mfma_f32_16x16x32_bf16 v[74:77], v[164:167], v[216:219], v[74:77]
	v_mfma_f32_16x16x32_bf16 v[118:121], v[168:171], v[184:187], v[118:121]
	v_mfma_f32_16x16x32_bf16 v[114:117], v[176:179], v[184:187], v[114:117]
	v_mfma_f32_16x16x32_bf16 v[102:105], v[168:171], v[192:195], v[102:105]
	v_mfma_f32_16x16x32_bf16 v[98:101], v[176:179], v[192:195], v[98:101]
	v_mfma_f32_16x16x32_bf16 v[86:89], v[168:171], v[204:207], v[86:89]
	v_mfma_f32_16x16x32_bf16 v[82:85], v[176:179], v[204:207], v[82:85]
	v_mfma_f32_16x16x32_bf16 v[70:73], v[168:171], v[212:215], v[70:73]
	v_mfma_f32_16x16x32_bf16 v[66:69], v[176:179], v[212:215], v[66:69]
	v_mfma_f32_16x16x32_bf16 v[118:121], v[172:175], v[188:191], v[118:121]
	v_mfma_f32_16x16x32_bf16 v[114:117], v[180:183], v[188:191], v[114:117]
	v_mfma_f32_16x16x32_bf16 v[102:105], v[172:175], v[200:203], v[102:105]
	v_mfma_f32_16x16x32_bf16 v[98:101], v[180:183], v[200:203], v[98:101]
	v_mfma_f32_16x16x32_bf16 v[86:89], v[172:175], v[208:211], v[86:89]
	v_mfma_f32_16x16x32_bf16 v[82:85], v[180:183], v[208:211], v[82:85]
	v_mfma_f32_16x16x32_bf16 v[70:73], v[172:175], v[216:219], v[70:73]
	v_mfma_f32_16x16x32_bf16 v[66:69], v[180:183], v[216:219], v[66:69]
	s_barrier
	s_add_i32 s43, s43, s30
	v_lshl_add_u64 v[220:221], s[24:25], 0, v[0:1]
	s_mov_b32 m0, s43
	ds_read_b128 v[184:187], v199 offset:16384
	ds_read_b128 v[188:191], v199 offset:17408
	ds_read_b128 v[192:195], v199 offset:18432
	ds_read_b128 v[200:203], v199 offset:19456
	ds_read_b128 v[204:207], v199 offset:20480
	ds_read_b128 v[208:211], v199 offset:21504
	ds_read_b128 v[212:215], v199 offset:22528
	ds_read_b128 v[216:219], v199 offset:23552
	global_load_lds_dwordx4 v[220:221], off
	s_add_i32 m0, s43, 0x2000
	s_add_u32 vcc_lo, s24, 0x80000
	v_lshl_add_u64 v[222:223], s[24:25], 0, v[126:127]
	s_addc_u32 vcc_hi, s25, 0
	s_add_i32 s43, s48, s30
	global_load_lds_dwordx4 v[222:223], off
	s_mov_b32 m0, s43
	v_lshl_add_u64 v[226:227], s[26:27], 0, v[126:127]
	global_load_lds_dwordx4 v0, vcc
	s_add_i32 m0, s43, 0x2000
	s_nop 0
	global_load_lds_dwordx4 v126, vcc
	s_mov_b32 m0, s31
	v_lshl_add_u64 v[224:225], s[26:27], 0, v[0:1]
	global_load_lds_dwordx4 v[224:225], off
	s_mov_b32 m0, s34
	s_nop 0
	global_load_lds_dwordx4 v[226:227], off
	s_waitcnt vmcnt(8) lgkmcnt(0)
	s_barrier
	v_mfma_f32_16x16x32_bf16 v[62:65], v[152:155], v[184:187], v[62:65]
	v_mfma_f32_16x16x32_bf16 v[58:61], v[160:163], v[184:187], v[58:61]
	v_mfma_f32_16x16x32_bf16 v[46:49], v[152:155], v[192:195], v[46:49]
	v_mfma_f32_16x16x32_bf16 v[42:45], v[160:163], v[192:195], v[42:45]
	v_mfma_f32_16x16x32_bf16 v[30:33], v[152:155], v[204:207], v[30:33]
	v_mfma_f32_16x16x32_bf16 v[26:29], v[160:163], v[204:207], v[26:29]
	v_mfma_f32_16x16x32_bf16 v[14:17], v[152:155], v[212:215], v[14:17]
	v_mfma_f32_16x16x32_bf16 v[10:13], v[160:163], v[212:215], v[10:13]
	v_mfma_f32_16x16x32_bf16 v[62:65], v[156:159], v[188:191], v[62:65]
	v_mfma_f32_16x16x32_bf16 v[58:61], v[164:167], v[188:191], v[58:61]
	v_mfma_f32_16x16x32_bf16 v[46:49], v[156:159], v[200:203], v[46:49]
	v_mfma_f32_16x16x32_bf16 v[42:45], v[164:167], v[200:203], v[42:45]
	v_mfma_f32_16x16x32_bf16 v[30:33], v[156:159], v[208:211], v[30:33]
	v_mfma_f32_16x16x32_bf16 v[26:29], v[164:167], v[208:211], v[26:29]
	v_mfma_f32_16x16x32_bf16 v[14:17], v[156:159], v[216:219], v[14:17]
	v_mfma_f32_16x16x32_bf16 v[10:13], v[164:167], v[216:219], v[10:13]
	v_mfma_f32_16x16x32_bf16 v[54:57], v[168:171], v[184:187], v[54:57]
	v_mfma_f32_16x16x32_bf16 v[50:53], v[176:179], v[184:187], v[50:53]
	v_mfma_f32_16x16x32_bf16 v[38:41], v[168:171], v[192:195], v[38:41]
	v_mfma_f32_16x16x32_bf16 v[34:37], v[176:179], v[192:195], v[34:37]
	v_mfma_f32_16x16x32_bf16 v[22:25], v[168:171], v[204:207], v[22:25]
	v_mfma_f32_16x16x32_bf16 v[18:21], v[176:179], v[204:207], v[18:21]
	v_mfma_f32_16x16x32_bf16 v[6:9], v[168:171], v[212:215], v[6:9]
	v_mfma_f32_16x16x32_bf16 v[2:5], v[176:179], v[212:215], v[2:5]
	v_mfma_f32_16x16x32_bf16 v[54:57], v[172:175], v[188:191], v[54:57]
	v_mfma_f32_16x16x32_bf16 v[50:53], v[180:183], v[188:191], v[50:53]
	v_mfma_f32_16x16x32_bf16 v[38:41], v[172:175], v[200:203], v[38:41]
	v_mfma_f32_16x16x32_bf16 v[34:37], v[180:183], v[200:203], v[34:37]
	v_mfma_f32_16x16x32_bf16 v[22:25], v[172:175], v[208:211], v[22:25]
	v_mfma_f32_16x16x32_bf16 v[18:21], v[180:183], v[208:211], v[18:21]
	v_mfma_f32_16x16x32_bf16 v[6:9], v[172:175], v[216:219], v[6:9]
	v_mfma_f32_16x16x32_bf16 v[2:5], v[180:183], v[216:219], v[2:5]
	s_barrier
; #define PG8_STAGE(bufoff, gbase, voff) do { _Pragma("unroll") for (int _i = 0; _i < 2; ++_i) \
;         __builtin_amdgcn_global_load_lds((const unsigned*)((const char*)(gbase) + (voff)[_i]), (PG8_LAS unsigned*)(lds + (bufoff) + ldsw + _i * 8192), 16, 0, 0); } while (0)
; #define PG8_LDA(dst, b, h) do { _Pragma("unroll") for (int m = 0; m < 4; ++m) _Pragma("unroll") for (int k = 0; k < 2; ++k) dst[m][k] = *(const PG8_LAS bf16x8*)(lds + PG8_SA(b, h) + aoff + m * 2048 + k * 1024); } while (0)
; #define PG8_LDB(dst, b, h) do { _Pragma("unroll") for (int n = 0; n < 2; ++n) _Pragma("unroll") for (int k = 0; k < 2; ++k) dst[n][k] = *(const PG8_LAS bf16x8*)(lds + PG8_SB(b, h) + boff + n * 2048 + k * 1024); } while (0)
; #define PG8_MMA(ai, bj, At, Bt) do { __builtin_amdgcn_s_setprio(1); _Pragma("unroll") for (int m = 0; m < 4; ++m) _Pragma("unroll") for (int n = 0; n < 2; ++n) _Pragma("unroll") for (int k = 0; k < 2; ++k) \
;         acc[ai][bj][m][n] = __builtin_amdgcn_mfma_f32_16x16x32_bf16(Bt[n][k], At[m][k], acc[ai][bj][m][n], 0, 0, 0); __builtin_amdgcn_s_setprio(0); } while (0)
; #define PG8_WAIT_V(n) asm volatile("s_waitcnt vmcnt(" #n ")" ::: "memory")
; #define PG8_WAIT_L(n) asm volatile("s_waitcnt lgkmcnt(" #n ")" ::: "memory")
; #define PG8_BAR __builtin_amdgcn_s_barrier()
; #define PG8_SCHED __builtin_amdgcn_sched_barrier(0)
; template <class Epi, class Sched, bool ALIGN_EPI = false, bool SP2 = false>
; __device__ __forceinline__ void gemm_phase(PG8_LAS unsigned char* lds, const Gemm g, const Sched& S, const Epi& E) {
;     ...
;             PG8_LDB(B0, 1, 0); PG8_LDB(B1, 1, 1); PG8_SCHED; PG8_LDA(At, 1, 0); PG8_STAGE(PG8_SA(0, 1), a2 + hstep, voffA);
;             PG8_WAIT_V(8); PG8_WAIT_L(0); PG8_BAR; PG8_MMA(0, 0, At, B0); PG8_MMA(0, 1, At, B1); PG8_BAR; PG8_SCHED;
;             PG8_LDA(At, 1, 1); PG8_STAGE(PG8_SB(1, 0), b3, voffB); PG8_STAGE(PG8_SB(1, 1), b3 + hstep, voffB); PG8_STAGE(PG8_SA(1, 0), a3, voffA);
;             PG8_WAIT_V(8); PG8_WAIT_L(0); PG8_BAR; PG8_MMA(1, 0, At, B0); PG8_MMA(1, 1, At, B1); PG8_BAR; PG8_SCHED;
	s_add_i32 s43, 0, 0x18000
	s_add_i32 s48, 0, 0x1c000
	v_add_u32_e32 v164, s43, v197
	v_add_u32_e32 v180, s48, v197
	ds_read_b128 v[152:155], v164
	ds_read_b128 v[156:159], v164 offset:1024
	ds_read_b128 v[160:163], v164 offset:2048
	ds_read_b128 v[164:167], v164 offset:3072
	ds_read_b128 v[168:171], v180
	ds_read_b128 v[172:175], v180 offset:1024
	ds_read_b128 v[176:179], v180 offset:2048
	ds_read_b128 v[180:183], v180 offset:3072
	s_add_u32 s26, s26, 0x80000
	s_addc_u32 s27, s27, 0
	s_mov_b32 m0, s35
	ds_read_b128 v[184:187], v199 offset:32768
	ds_read_b128 v[188:191], v199 offset:33792
	ds_read_b128 v[192:195], v199 offset:34816
	ds_read_b128 v[200:203], v199 offset:35840
	ds_read_b128 v[204:207], v199 offset:36864
	ds_read_b128 v[208:211], v199 offset:37888
	ds_read_b128 v[212:215], v199 offset:38912
	ds_read_b128 v[216:219], v199 offset:39936
	global_load_lds_dwordx4 v0, s[26:27]
	s_mov_b32 m0, s76
	s_nop 0
	global_load_lds_dwordx4 v126, s[26:27]
	s_waitcnt vmcnt(8) lgkmcnt(0)
	s_barrier
	v_mfma_f32_16x16x32_bf16 v[144:147], v[152:155], v[184:187], v[144:147]
	v_mfma_f32_16x16x32_bf16 v[122:125], v[160:163], v[184:187], v[122:125]
	v_mfma_f32_16x16x32_bf16 v[110:113], v[152:155], v[192:195], v[110:113]
	v_mfma_f32_16x16x32_bf16 v[106:109], v[160:163], v[192:195], v[106:109]
	v_mfma_f32_16x16x32_bf16 v[94:97], v[152:155], v[204:207], v[94:97]
	v_mfma_f32_16x16x32_bf16 v[90:93], v[160:163], v[204:207], v[90:93]
	v_mfma_f32_16x16x32_bf16 v[78:81], v[152:155], v[212:215], v[78:81]
	v_mfma_f32_16x16x32_bf16 v[74:77], v[160:163], v[212:215], v[74:77]
	v_mfma_f32_16x16x32_bf16 v[144:147], v[156:159], v[188:191], v[144:147]
	v_mfma_f32_16x16x32_bf16 v[122:125], v[164:167], v[188:191], v[122:125]
	v_mfma_f32_16x16x32_bf16 v[110:113], v[156:159], v[200:203], v[110:113]
	v_mfma_f32_16x16x32_bf16 v[106:109], v[164:167], v[200:203], v[106:109]
	v_mfma_f32_16x16x32_bf16 v[94:97], v[156:159], v[208:211], v[94:97]
	v_mfma_f32_16x16x32_bf16 v[90:93], v[164:167], v[208:211], v[90:93]
	v_mfma_f32_16x16x32_bf16 v[78:81], v[156:159], v[216:219], v[78:81]
	v_mfma_f32_16x16x32_bf16 v[74:77], v[164:167], v[216:219], v[74:77]
	v_mfma_f32_16x16x32_bf16 v[118:121], v[168:171], v[184:187], v[118:121]
	v_mfma_f32_16x16x32_bf16 v[114:117], v[176:179], v[184:187], v[114:117]
	v_mfma_f32_16x16x32_bf16 v[102:105], v[168:171], v[192:195], v[102:105]
	v_mfma_f32_16x16x32_bf16 v[98:101], v[176:179], v[192:195], v[98:101]
	v_mfma_f32_16x16x32_bf16 v[86:89], v[168:171], v[204:207], v[86:89]
	v_mfma_f32_16x16x32_bf16 v[82:85], v[176:179], v[204:207], v[82:85]
	v_mfma_f32_16x16x32_bf16 v[70:73], v[168:171], v[212:215], v[70:73]
	v_mfma_f32_16x16x32_bf16 v[66:69], v[176:179], v[212:215], v[66:69]
	v_mfma_f32_16x16x32_bf16 v[118:121], v[172:175], v[188:191], v[118:121]
	v_mfma_f32_16x16x32_bf16 v[114:117], v[180:183], v[188:191], v[114:117]
	v_mfma_f32_16x16x32_bf16 v[102:105], v[172:175], v[200:203], v[102:105]
	v_mfma_f32_16x16x32_bf16 v[98:101], v[180:183], v[200:203], v[98:101]
	v_mfma_f32_16x16x32_bf16 v[86:89], v[172:175], v[208:211], v[86:89]
	v_mfma_f32_16x16x32_bf16 v[82:85], v[180:183], v[208:211], v[82:85]
	v_mfma_f32_16x16x32_bf16 v[70:73], v[172:175], v[216:219], v[70:73]
	v_mfma_f32_16x16x32_bf16 v[66:69], v[180:183], v[216:219], v[66:69]
	s_barrier
	s_add_i32 s26, s43, s30
	v_lshl_add_u64 v[220:221], v[220:221], 0, s[64:65]
	s_mov_b32 m0, s26
	ds_read_b128 v[184:187], v199 offset:49152
	ds_read_b128 v[188:191], v199 offset:50176
	ds_read_b128 v[192:195], v199 offset:51200
	ds_read_b128 v[200:203], v199 offset:52224
	ds_read_b128 v[204:207], v199 offset:53248
	ds_read_b128 v[208:211], v199 offset:54272
	ds_read_b128 v[212:215], v199 offset:55296
	ds_read_b128 v[216:219], v199 offset:56320
	global_load_lds_dwordx4 v[220:221], off
	s_add_i32 m0, s26, 0x2000
	s_add_u32 s24, s24, 0x80080
	v_lshl_add_u64 v[220:221], v[222:223], 0, s[64:65]
	s_addc_u32 s25, s25, 0
	s_add_i32 s26, s48, s30
	global_load_lds_dwordx4 v[220:221], off
	s_mov_b32 m0, s26
	s_nop 0
	global_load_lds_dwordx4 v0, s[24:25]
	s_add_i32 m0, s26, 0x2000
	s_nop 0
	global_load_lds_dwordx4 v126, s[24:25]
	s_mov_b32 m0, s82
	v_lshl_add_u64 v[220:221], v[224:225], 0, s[64:65]
	global_load_lds_dwordx4 v[220:221], off
	s_mov_b32 m0, s83
	v_lshl_add_u64 v[220:221], v[226:227], 0, s[64:65]
	global_load_lds_dwordx4 v[220:221], off
	s_waitcnt vmcnt(8) lgkmcnt(0)
	s_barrier
	v_mfma_f32_16x16x32_bf16 v[62:65], v[152:155], v[184:187], v[62:65]
	v_mfma_f32_16x16x32_bf16 v[58:61], v[160:163], v[184:187], v[58:61]
	v_mfma_f32_16x16x32_bf16 v[46:49], v[152:155], v[192:195], v[46:49]
	v_mfma_f32_16x16x32_bf16 v[42:45], v[160:163], v[192:195], v[42:45]
	v_mfma_f32_16x16x32_bf16 v[30:33], v[152:155], v[204:207], v[30:33]
	v_mfma_f32_16x16x32_bf16 v[26:29], v[160:163], v[204:207], v[26:29]
	v_mfma_f32_16x16x32_bf16 v[14:17], v[152:155], v[212:215], v[14:17]
	v_mfma_f32_16x16x32_bf16 v[10:13], v[160:163], v[212:215], v[10:13]
	v_mfma_f32_16x16x32_bf16 v[62:65], v[156:159], v[188:191], v[62:65]
	v_mfma_f32_16x16x32_bf16 v[58:61], v[164:167], v[188:191], v[58:61]
	v_mfma_f32_16x16x32_bf16 v[46:49], v[156:159], v[200:203], v[46:49]
	v_mfma_f32_16x16x32_bf16 v[42:45], v[164:167], v[200:203], v[42:45]
	v_mfma_f32_16x16x32_bf16 v[30:33], v[156:159], v[208:211], v[30:33]
	v_mfma_f32_16x16x32_bf16 v[26:29], v[164:167], v[208:211], v[26:29]
	v_mfma_f32_16x16x32_bf16 v[14:17], v[156:159], v[216:219], v[14:17]
	v_mfma_f32_16x16x32_bf16 v[10:13], v[164:167], v[216:219], v[10:13]
	v_mfma_f32_16x16x32_bf16 v[54:57], v[168:171], v[184:187], v[54:57]
	v_mfma_f32_16x16x32_bf16 v[50:53], v[176:179], v[184:187], v[50:53]
	v_mfma_f32_16x16x32_bf16 v[38:41], v[168:171], v[192:195], v[38:41]
	v_mfma_f32_16x16x32_bf16 v[34:37], v[176:179], v[192:195], v[34:37]
	v_mfma_f32_16x16x32_bf16 v[22:25], v[168:171], v[204:207], v[22:25]
	v_mfma_f32_16x16x32_bf16 v[18:21], v[176:179], v[204:207], v[18:21]
	v_mfma_f32_16x16x32_bf16 v[6:9], v[168:171], v[212:215], v[6:9]
	v_mfma_f32_16x16x32_bf16 v[2:5], v[176:179], v[212:215], v[2:5]
	v_mfma_f32_16x16x32_bf16 v[54:57], v[172:175], v[188:191], v[54:57]
	v_mfma_f32_16x16x32_bf16 v[50:53], v[180:183], v[188:191], v[50:53]
	v_mfma_f32_16x16x32_bf16 v[38:41], v[172:175], v[200:203], v[38:41]
	v_mfma_f32_16x16x32_bf16 v[34:37], v[180:183], v[200:203], v[34:37]
	v_mfma_f32_16x16x32_bf16 v[22:25], v[172:175], v[208:211], v[22:25]
	v_mfma_f32_16x16x32_bf16 v[18:21], v[180:183], v[208:211], v[18:21]
	v_mfma_f32_16x16x32_bf16 v[6:9], v[172:175], v[216:219], v[6:9]
	v_mfma_f32_16x16x32_bf16 v[2:5], v[180:183], v[216:219], v[2:5]
	s_barrier
	s_add_i32 s42, s42, 2
	s_add_u32 s0, s0, 0x100
	s_addc_u32 s1, s1, 0
	s_add_u32 s40, s40, 0x100
	s_addc_u32 s41, s41, 0
	s_cmp_gt_u32 s42, 29
	s_cbranch_scc0 .LBB0_963
	s_and_b64 vcc, exec, s[14:15]
	s_cbranch_vccz .LBB0_966
	s_barrier
